# s5_scan: idle wave 1 walks the same rows issuing loads ahead of the scanning wave (cache warm-up helper)
# baseline (speedup 1.0000x reference)
.Ls5h_entry:
	s_mov_b32 s62, s68
	s_cmpk_gt_i32 s62, 0xff
	s_cbranch_scc1 .Ls5h_done
	v_and_b32_e32 v0, 63, v12
	v_lshlrev_b32_e32 v0, 2, v0
	v_readlane_b32 s21, v254, 19
.Ls5h_item:
	s_and_b32 s0, s62, 15
	s_bfe_u32 s1, s62, 0x30004
	s_lshr_b32 s2, s62, 7
	s_lshl_b32 s0, s0, 12
	s_lshl_b32 s1, s1, 9
	s_add_i32 s0, s0, s1
	s_cmp_eq_u32 s2, 0
	s_cselect_b32 s1, 0, 0x1ff
	s_add_i32 s0, s0, s1
	s_lshl_b32 s0, s0, 9
	s_lshl_b32 s3, s2, 8
	s_add_i32 s0, s0, s3
	s_add_u32 s22, s78, 0x3a800000
	s_addc_u32 s23, s79, 0
	s_add_u32 s22, s22, s0
	s_addc_u32 s23, s23, 0
	v_mov_b32_e32 v3, s23
	v_add_co_u32_e32 v2, vcc, s22, v0
	s_nop 1
	v_addc_co_u32_e32 v3, vcc, 0, v3, vcc
	s_movk_i32 s24, 64
	s_cmp_eq_u32 s2, 0
	s_cbranch_scc0 .Ls5h_rev
	s_movk_i32 s0, 0x1000
	s_mov_b32 s1, 0
.Ls5h_fwd:
	global_load_dword v4, v[2:3], off
	global_load_dword v5, v[2:3], off offset:512
	global_load_dword v6, v[2:3], off offset:1024
	global_load_dword v7, v[2:3], off offset:1536
	global_load_dword v8, v[2:3], off offset:2048
	global_load_dword v9, v[2:3], off offset:2560
	global_load_dword v10, v[2:3], off offset:3072
	global_load_dword v11, v[2:3], off offset:3584
	v_lshl_add_u64 v[2:3], v[2:3], 0, s[0:1]
	s_sub_i32 s24, s24, 1
	s_cmp_lg_u32 s24, 0
	s_cbranch_scc1 .Ls5h_fwd
	s_branch .Ls5h_next
.Ls5h_rev:
	s_mov_b32 s0, 0xfffff000
	s_mov_b32 s1, -1
.Ls5h_rl:
	global_load_dword v4, v[2:3], off
	global_load_dword v5, v[2:3], off offset:-512
	global_load_dword v6, v[2:3], off offset:-1024
	global_load_dword v7, v[2:3], off offset:-1536
	global_load_dword v8, v[2:3], off offset:-2048
	global_load_dword v9, v[2:3], off offset:-2560
	global_load_dword v10, v[2:3], off offset:-3072
	global_load_dword v11, v[2:3], off offset:-3584
	v_lshl_add_u64 v[2:3], v[2:3], 0, s[0:1]
	s_sub_i32 s24, s24, 1
	s_cmp_lg_u32 s24, 0
	s_cbranch_scc1 .Ls5h_rl
.Ls5h_next:
	s_add_i32 s62, s62, s21
	s_cmpk_lt_i32 s62, 0x100
	s_cbranch_scc1 .Ls5h_item
.Ls5h_done:
	s_waitcnt vmcnt(0)
	s_mov_b64 s[0:1], exec
	s_branch .LBB0_597

.LBB0_590:
	s_or_b64 exec, exec, s[0:1]
	v_mov_b32_e32 v12, v181
	s_nop 0
	v_readfirstlane_b32 s2, v12
	s_lshr_b32 s2, s2, 6
	s_cmp_eq_u32 s2, 1
	s_cbranch_scc1 .Ls5h_entry
	v_cmp_gt_i32_e32 vcc, 64, v12
	s_and_saveexec_b64 s[0:1], vcc
	s_cbranch_execz .LBB0_597
	s_mov_b64 s[2:3], 0
	s_mov_b64 s[20:21], 0
	s_mov_b32 s62, s68
	s_cmpk_gt_i32 s62, 0xff
	s_cbranch_scc1 .LBB0_597
	s_add_u32 s63, s78, s20
	s_addc_u32 s64, s79, s21
	s_add_u32 s2, s78, s2
	s_waitcnt lgkmcnt(0)
	v_lshlrev_b32_e32 v2, 1, v12
	s_addc_u32 s3, s79, s3
	v_ashrrev_i32_e32 v3, 31, v2
	v_readlane_b32 s20, v254, 39
	v_lshl_add_u64 v[0:1], v[2:3], 1, s[2:3]
	s_mov_b64 s[2:3], 0x3a800000
	s_lshl_b32 s65, s20, 5
	v_lshl_add_u64 v[0:1], v[0:1], 0, s[2:3]
	v_lshlrev_b64 v[2:3], 1, v[2:3]
	v_readlane_b32 s21, v254, 40
